# v22 + w_up / w_dn weight transposes moved out of phase 0 into the split-phase in-proj->mixer barrier windows of batches 2,3 (all four such barriers now split-phase)
# speedup vs baseline: 1.0357x; 1.0100x over previous
; __device__ __forceinline__ KParams kparams() { unsigned long long a = (unsigned long long)__builtin_amdgcn_kernarg_segment_ptr(); asm volatile("" : "+s"(a)); return (KParams)a; }
; __global__ void __launch_bounds__(512, 2) mega(Params p_unused) {
;     ...
;     {
;         KParams kp = kparams(); unsigned char* ws = kp->ws;
;         transpose_w(wv, lds, kp->w_in, WSP(bf16_t, WS_WIN), DM, INW, kp->norm1_g, C_RK, C_RK + 1024, 0.0625f);
;         transpose_w(wv, lds, kp->w_pa, WSP(bf16_t, WS_WPA), 512, DM, nullptr, 0, 0, 1.f);
;         transpose_w(wv, lds, kp->w_pb, WSP(bf16_t, WS_WPB), 2048, DM, nullptr, 0, 0, 1.f);
;         transpose_w(wv, lds, kp->w_out, WSP(bf16_t, WS_WOUT), DM, DM, nullptr, 0, 0, 1.f);
;         transpose_w(wv, lds, kp->w_up, WSP(bf16_t, WS_WUP), DM, DFF, kp->norm2_g, 0, 0, 1.f);
;         transpose_w(wv, lds, kp->w_dn, WSP(bf16_t, WS_WDN), DFF, DM, nullptr, 0, 0, 1.f);
;         prep_x(wv, kp->x, WSP(bf16_t, WS_OR));
;     }
.LBB0_33:
.LBB0_55:
	v_mbcnt_lo_u32_b32 v2, -1, 0
	v_mbcnt_hi_u32_b32 v2, -1, v2
	s_mov_b32 s14, 0x8000
	v_add_u32_e32 v2, s53, v2
	v_ashrrev_i32_e32 v3, 6, v2
	v_lshl_add_u32 v78, s66, 3, v3
	v_cmp_gt_i32_e32 vcc, s14, v78
	v_mbcnt_lo_u32_b32 v2, -1, 0
	v_mbcnt_hi_u32_b32 v2, -1, v2
	s_and_saveexec_b64 s[6:7], vcc
	s_cbranch_execz .LBB0_70
	s_load_dwordx2 s[0:1], s[2:3], 0x0
	v_lshlrev_b32_e32 v2, 2, v2
	s_waitcnt lgkmcnt(0)
	s_add_u32 s10, s10, 0x15400000
	v_and_b32_e32 v66, 0xfc, v2
	s_addc_u32 s11, s11, 0
	s_lshl_b32 s15, s54, 3
	v_mov_b32_e32 v69, 0
	v_lshlrev_b32_e32 v68, 2, v66
	v_lshl_add_u64 v[70:71], s[0:1], 0, v[68:69]
	v_bfrev_b32_e32 v3, 0.5
	s_movk_i32 s0, 0x80
	s_add_i32 s19, s15, s15
	v_bitop3_b32 v67, v2, 4, v3 bitop3:0x6c
	v_bitop3_b32 v80, v2, 8, v3 bitop3:0x6c
	v_bitop3_b32 v81, v2, 16, v3 bitop3:0x6c
	v_bitop3_b32 v82, v2, 32, v3 bitop3:0x6c
	v_bitop3_b32 v83, v2, 64, v3 bitop3:0x6c
	v_bitop3_b32 v84, v2, s0, v3 bitop3:0x6c
	s_lshl_b32 s16, s54, 4
	s_mul_i32 s17, s54, 24
	s_mov_b64 s[12:13], 0
	v_mov_b32_e32 v85, 0x358637bd
	s_mov_b32 s18, 0x800000
	s_add_i32 s19, s19, s15
	s_movk_i32 s20, 0x3fff
	s_branch .LBB0_58

; #define LAS __attribute__((address_space(3)))
; __device__ __forceinline__ void transpose_w(const int wv, LAS unsigned char* lds, const float* __restrict__ w, bf16_t* __restrict__ wt, int K, int N, const float* __restrict__ gk, int slo, int shi, float scale) {
;     const int tk = K / 64, tn = N / 64, nt = tk * tn;
;     const int t = TIDX, nl = t & 63, kg = t >> 6, n2 = t >> 3, kc = t & 7;
;     for (int tile = blockIdx.x; tile < nt; tile += gridDim.x) {
;         const int kt0 = (tile % tk) * 64, nb0 = (tile / tk) * 64;
;         const int k0 = kt0 + kg * 8, n = nb0 + nl;
;         float v[8];
; #pragma unroll
;         for (int j = 0; j < 8; ++j) { float g = gk ? gk[k0 + j] : 1.0f; v[j] = w[(size_t)(k0 + j) * N + n] * g; }
.Lxp_70:
	s_or_b64 exec, exec, s[6:7]
	s_branch .Lwin_wait
.Lwin_t:
	s_mov_b64 s[2:3], s[56:57]
	s_load_dwordx2 s[10:11], s[56:57], 0x70
	s_waitcnt lgkmcnt(0)
	s_cmp_eq_u32 s79, 2
	s_cbranch_scc0 .Lwin_dn
	s_cmpk_lt_i32 s66, 0x400
	s_cselect_b64 s[12:13], -1, 0
	s_cmpk_gt_i32 s66, 0x3ff
	v_mbcnt_lo_u32_b32 v2, -1, 0
	v_mbcnt_hi_u32_b32 v2, -1, v2
	s_cbranch_scc1 .Lwin_wait
	s_load_dwordx4 s[4:7], s[2:3], 0x50
	s_waitcnt lgkmcnt(0)
	s_add_u32 s14, s10, 0x2000000
	s_addc_u32 s15, s11, 0
	v_add_u32_e32 v3, s53, v2
	v_ashrrev_i32_e32 v11, 3, v3
	v_ashrrev_i32_e32 v3, 6, v3
	s_cmp_lg_u64 s[4:5], 0
	s_movk_i32 s16, 0x90
	v_and_b32_e32 v10, 63, v2
	v_and_b32_e32 v2, 7, v2
	v_lshlrev_b32_e32 v12, 3, v3
	s_cselect_b64 s[0:1], -1, 0
	v_lshlrev_b32_e32 v5, 4, v3
	v_mul_lo_u32 v3, v11, s16
	v_mad_u32_u24 v4, v10, s16, 0
	v_add_u32_e32 v6, 0, v3
	v_lshlrev_b32_e32 v7, 4, v2
	v_lshlrev_b32_e32 v2, 3, v2
	v_cndmask_b32_e64 v8, 0, 1, s[0:1]
	v_mov_b32_e32 v3, 0
	s_lshl_b32 s16, s66, 6
	s_lshl_b32 s17, s54, 6
	v_cmp_ne_u32_e64 s[0:1], 1, v8
	v_add_u32_e32 v13, v4, v5
	v_add_u32_e32 v14, v6, v7
	v_lshlrev_b32_e32 v2, 1, v2
	s_mov_b32 s18, s66
	s_branch .Lwu_36

; #define LAS __attribute__((address_space(3)))
; __device__ __forceinline__ unsigned cvt_pk_bf16(float lo, float hi) { unsigned r; asm volatile("v_cvt_pk_bf16_f32 %0, %1, %2" : "=v"(r) : "v"(lo), "v"(hi)); return r; }
; __device__ __forceinline__ void transpose_w(const int wv, LAS unsigned char* lds, const float* __restrict__ w, bf16_t* __restrict__ wt, int K, int N, const float* __restrict__ gk, int slo, int shi, float scale) {
;     const int tk = K / 64, tn = N / 64, nt = tk * tn;
;     const int t = TIDX, nl = t & 63, kg = t >> 6, n2 = t >> 3, kc = t & 7;
;     for (int tile = blockIdx.x; tile < nt; tile += gridDim.x) {
;         const int kt0 = (tile % tk) * 64, nb0 = (tile / tk) * 64;
;         const int k0 = kt0 + kg * 8, n = nb0 + nl;
;         float v[8];
; #pragma unroll
;         for (int j = 0; j < 8; ++j) { float g = gk ? gk[k0 + j] : 1.0f; v[j] = w[(size_t)(k0 + j) * N + n] * g; }
;         if (n >= slo && n < shi) {
; #pragma unroll
;             for (int j = 0; j < 8; ++j) v[j] *= scale;
;         }
;         u32x4 o; o.x = cvt_pk_bf16(v[0], v[1]); o.y = cvt_pk_bf16(v[2], v[3]); o.z = cvt_pk_bf16(v[4], v[5]); o.w = cvt_pk_bf16(v[6], v[7]);
;         *(LAS u32x4*)(lds + nl * 144 + kg * 16) = o;
;         __syncthreads();
;         *(u32x4*)(wt + (size_t)(nb0 + n2) * K + kt0 + kc * 8) = *(const LAS u32x4*)(lds + n2 * 144 + kc * 16);
;         __syncthreads();
;     }
; }
.Lwu_50:
	v_add_u32_e32 v28, 6, v4
	v_ashrrev_i32_e32 v29, 31, v28
	v_lshlrev_b64 v[28:29], 14, v[28:29]
	v_lshl_add_u64 v[28:29], v[6:7], 0, v[28:29]
	global_load_dword v28, v[28:29], off nt
	s_and_b64 vcc, exec, s[0:1]
	s_cbranch_vccnz .Lwu_35
	global_load_dword v21, v[8:9], off offset:28 nt
	s_branch .Lwu_35
	s_branch .Lwin_wait
.Lwin_dn:
	s_mov_b64 s[12:13], -1
	s_andn2_b64 vcc, exec, s[12:13]
	v_mbcnt_lo_u32_b32 v2, -1, 0
	v_mbcnt_hi_u32_b32 v2, -1, v2
	s_cbranch_vccnz .Lwin_wait
	s_load_dwordx2 s[0:1], s[2:3], 0x60
	v_add_u32_e32 v3, s53, v2
	v_ashrrev_i32_e32 v5, 3, v3
	v_ashrrev_i32_e32 v3, 6, v3
	s_movk_i32 s6, 0x90
	v_and_b32_e32 v4, 63, v2
	v_and_b32_e32 v2, 7, v2
	v_lshlrev_b32_e32 v6, 3, v3
	v_lshlrev_b32_e32 v8, 4, v3
	v_mul_lo_u32 v3, v5, s6
	s_waitcnt lgkmcnt(0)
	s_add_u32 s4, s10, 0x2800000
	v_mad_u32_u24 v7, v4, s6, 0
	v_add_u32_e32 v9, 0, v3
	v_lshlrev_b32_e32 v10, 4, v2
	v_lshlrev_b32_e32 v2, 3, v2
	s_addc_u32 s5, s11, 0
	v_mov_b32_e32 v3, 0
	s_lshl_b32 s12, s66, 6
	s_lshl_b32 s13, s54, 6
	v_add_u32_e32 v7, v7, v8
	v_add_u32_e32 v8, v9, v10
	v_lshlrev_b32_e32 v2, 1, v2
	s_mov_b32 s14, s66
.Lwd_54:
	s_ashr_i32 s6, s14, 31
	s_lshr_b32 s6, s6, 26
	s_add_i32 s6, s14, s6
	s_lshl_b32 s7, s6, 6
	s_and_b32 s15, s6, 0xffffffc0
	s_and_b32 s6, s7, 0xfffff000
	s_sub_i32 s6, s12, s6
	v_or_b32_e32 v10, s15, v4
	v_add_u32_e32 v12, s6, v6
	v_ashrrev_i32_e32 v11, 31, v10
	v_ashrrev_i32_e32 v13, 31, v12
	v_add_u32_e32 v14, 1, v12
	v_add_u32_e32 v16, 2, v12
	v_add_u32_e32 v18, 3, v12
	v_add_u32_e32 v20, 4, v12
	v_add_u32_e32 v22, 5, v12
	v_add_u32_e32 v24, 6, v12
	v_add_u32_e32 v26, 7, v12
	v_lshl_add_u64 v[10:11], v[10:11], 2, s[0:1]
	v_lshlrev_b64 v[12:13], 12, v[12:13]
	v_ashrrev_i32_e32 v15, 31, v14
	v_ashrrev_i32_e32 v17, 31, v16
	v_ashrrev_i32_e32 v19, 31, v18
	v_ashrrev_i32_e32 v21, 31, v20
	v_ashrrev_i32_e32 v23, 31, v22
	v_ashrrev_i32_e32 v25, 31, v24
	v_ashrrev_i32_e32 v27, 31, v26
	v_lshl_add_u64 v[12:13], v[10:11], 0, v[12:13]
	v_lshlrev_b64 v[14:15], 12, v[14:15]
	v_lshlrev_b64 v[16:17], 12, v[16:17]
	v_lshlrev_b64 v[18:19], 12, v[18:19]
	v_lshlrev_b64 v[20:21], 12, v[20:21]
	v_lshlrev_b64 v[22:23], 12, v[22:23]
	v_lshlrev_b64 v[24:25], 12, v[24:25]
	v_lshlrev_b64 v[26:27], 12, v[26:27]
	v_lshl_add_u64 v[14:15], v[10:11], 0, v[14:15]
	v_lshl_add_u64 v[16:17], v[10:11], 0, v[16:17]
	v_lshl_add_u64 v[18:19], v[10:11], 0, v[18:19]
	v_lshl_add_u64 v[20:21], v[10:11], 0, v[20:21]
	v_lshl_add_u64 v[22:23], v[10:11], 0, v[22:23]
	v_lshl_add_u64 v[24:25], v[10:11], 0, v[24:25]
	v_lshl_add_u64 v[10:11], v[10:11], 0, v[26:27]
	global_load_dword v9, v[12:13], off nt
	global_load_dword v26, v[14:15], off nt
	global_load_dword v27, v[18:19], off nt
	global_load_dword v28, v[24:25], off nt
	global_load_dword v29, v[20:21], off nt
	global_load_dword v30, v[16:17], off nt
	global_load_dword v31, v[22:23], off nt
	global_load_dword v32, v[10:11], off nt
	v_add_u32_e32 v10, s15, v5
	v_ashrrev_i32_e32 v11, 31, v10
	v_lshlrev_b64 v[10:11], 13, v[10:11]
	s_ashr_i32 s7, s6, 31
	v_lshl_add_u64 v[10:11], s[4:5], 0, v[10:11]
	v_lshl_add_u64 v[14:15], s[6:7], 1, v[10:11]
	s_add_i32 s14, s14, s54
	s_add_i32 s12, s12, s13
	s_cmpk_lt_i32 s14, 0x400
	v_lshl_add_u64 v[14:15], v[14:15], 0, v[2:3]
	s_waitcnt vmcnt(6)
	v_cvt_pk_bf16_f32 v10, v9, v26
	s_waitcnt vmcnt(2)
	v_cvt_pk_bf16_f32 v11, v30, v27
	s_waitcnt vmcnt(1)
	v_cvt_pk_bf16_f32 v12, v29, v31
	s_waitcnt vmcnt(0)
	v_cvt_pk_bf16_f32 v13, v28, v32
	ds_write_b128 v7, v[10:13]
	s_waitcnt lgkmcnt(0)
	s_barrier
	ds_read_b128 v[10:13], v8
	s_waitcnt lgkmcnt(0)
	global_store_dwordx4 v[14:15], v[10:13], off
	s_barrier
	s_cbranch_scc1 .Lwd_54
.Lwin_wait:
	s_cmp_eq_u32 s101, 0
	s_cbranch_scc1 .Lgwb1_done
	v_mov_b32_e32 v222, s98
	v_mov_b32_e32 v223, s99

; __device__ __forceinline__ KParams kparams() { unsigned long long a = (unsigned long long)__builtin_amdgcn_kernarg_segment_ptr(); asm volatile("" : "+s"(a)); return (KParams)a; }
; __device__ __forceinline__ void xcd_barrier(const int wv, const XcdBarrier& b) {
;     ...
;     __syncthreads();
; }
; __global__ void __launch_bounds__(512, 2) mega(Params p_unused) {
;     ...
;         {
;             KParams kp = kparams(); unsigned char* ws = kp->ws;
;             for (int j = blockIdx.x; j < 512; j += gridDim.x) reta_item(wv, lds, ldsb, WSP(bf16_t, WS_R0), WSP(bf16_t, WS_KV), j);
;         }
.Lgwb1_done:
	s_barrier
.LBB0_366:
	v_readlane_b32 s2, v253, 0
	v_readlane_b32 s3, v253, 1
	s_mov_b64 s[0:1], s[56:57]
	s_andn2_b64 vcc, exec, s[2:3]
	v_cndmask_b32_e64 v1, 0, 1, s[2:3]
	v_cmp_ne_u32_e64 s[4:5], 1, v1
	s_nop 1
	v_writelane_b32 v254, s4, 22
	s_nop 1
	v_writelane_b32 v254, s5, 23
	s_cbranch_vccnz .LBB0_373
	s_load_dwordx2 s[2:3], s[0:1], 0x70
	s_mov_b32 s8, s66
	s_waitcnt lgkmcnt(0)
	s_add_u32 s0, s2, 0x8c00000
	s_addc_u32 s1, s3, 0
	s_add_u32 s6, s2, 0x4c00000
	s_addc_u32 s7, s3, 0
